# conv: LayerNorm partial reductions of each chain pair run together (four bpermutes per step, shared waits, one lane-0 write block)
# speedup vs baseline: 1.0070x; 1.0052x over previous
; DI void conv_item(const Params& p, char* lds, int t0, int tid) {
;     ...
;     float za[38], zb[38];
; #pragma unroll
;     for (int rr = 0; rr < 38; ++rr) {
;       const unsigned u = zl[(ps * 8 + rr) * 256 + tid];
;       za[rr] = __uint_as_float(u << 16); zb[rr] = __uint_as_float(u & 0xffff0000u);
;     }
;     float ya[8], yb[8];
; #pragma unroll
;     for (int i = 0; i < 8; ++i) {
;       float a = bias.x, b = bias.y;
; #pragma unroll
;       for (int j = 0; j < 31; ++j) { a += wa[j] * za[i + j]; b += wb[j] * zb[i + j]; }
.LBB0_196:
	ds_read2st64_b32 v[2:3], v238 offset1:4
	ds_read2st64_b32 v[4:5], v238 offset0:8 offset1:12
	ds_read2st64_b32 v[160:161], v238 offset0:40 offset1:44
	ds_read2st64_b32 v[170:171], v238 offset0:56 offset1:60
	ds_read2st64_b32 v[178:179], v238 offset0:72 offset1:76
	s_waitcnt lgkmcnt(4)
	v_lshlrev_b32_e32 v204, 16, v2
	v_and_b32_e32 v205, 0xffff0000, v2
	v_lshlrev_b32_e32 v156, 16, v3
	v_and_b32_e32 v157, 0xffff0000, v3
	ds_read2st64_b32 v[2:3], v238 offset0:16 offset1:20
	s_waitcnt lgkmcnt(4)
	v_lshlrev_b32_e32 v158, 16, v4
	v_and_b32_e32 v159, 0xffff0000, v4
	v_lshlrev_b32_e32 v164, 16, v5
	v_and_b32_e32 v165, 0xffff0000, v5
	s_waitcnt lgkmcnt(0)
	v_lshlrev_b32_e32 v148, 16, v2
	v_and_b32_e32 v149, 0xffff0000, v2
	v_lshlrev_b32_e32 v150, 16, v3
	v_and_b32_e32 v151, 0xffff0000, v3
	ds_read2st64_b32 v[2:3], v238 offset0:32 offset1:36
	ds_read2st64_b32 v[4:5], v238 offset0:24 offset1:28
	v_lshlrev_b32_e32 v154, 16, v160
	v_and_b32_e32 v155, 0xffff0000, v160
	v_lshlrev_b32_e32 v160, 16, v161
	s_waitcnt lgkmcnt(1)
	v_lshlrev_b32_e32 v6, 16, v2
	v_and_b32_e32 v7, 0xffff0000, v2
	v_lshlrev_b32_e32 v8, 16, v3
	v_and_b32_e32 v9, 0xffff0000, v3
	ds_read2st64_b32 v[2:3], v238 offset0:48 offset1:52
	s_waitcnt lgkmcnt(1)
	v_lshlrev_b32_e32 v152, 16, v4
	v_and_b32_e32 v153, 0xffff0000, v4
	v_lshlrev_b32_e32 v4, 16, v5
	v_and_b32_e32 v5, 0xffff0000, v5
	s_waitcnt lgkmcnt(0)
	v_lshlrev_b32_e32 v162, 16, v2
	v_and_b32_e32 v163, 0xffff0000, v2
	v_lshlrev_b32_e32 v166, 16, v3
	v_and_b32_e32 v167, 0xffff0000, v3
	ds_read2st64_b32 v[2:3], v238 offset0:64 offset1:68
	v_and_b32_e32 v161, 0xffff0000, v161
	v_lshlrev_b32_e32 v168, 16, v170
	v_and_b32_e32 v169, 0xffff0000, v170
	v_lshlrev_b32_e32 v170, 16, v171
	s_waitcnt lgkmcnt(0)
	v_lshlrev_b32_e32 v172, 16, v2
	v_and_b32_e32 v173, 0xffff0000, v2
	v_lshlrev_b32_e32 v174, 16, v3
	v_and_b32_e32 v175, 0xffff0000, v3
	ds_read2st64_b32 v[2:3], v238 offset0:80 offset1:84
	v_and_b32_e32 v171, 0xffff0000, v171
	ds_read2st64_b32 v[186:187], v238 offset0:88 offset1:92
	v_lshlrev_b32_e32 v176, 16, v178
	v_and_b32_e32 v177, 0xffff0000, v178
	s_waitcnt lgkmcnt(1)
	v_lshlrev_b32_e32 v180, 16, v2
	v_and_b32_e32 v181, 0xffff0000, v2
	v_lshlrev_b32_e32 v182, 16, v3
	v_and_b32_e32 v183, 0xffff0000, v3
	ds_read2st64_b32 v[2:3], v238 offset0:96 offset1:100
	v_lshlrev_b32_e32 v178, 16, v179
	v_and_b32_e32 v179, 0xffff0000, v179
	ds_read2st64_b32 v[194:195], v238 offset0:104 offset1:108
	s_waitcnt lgkmcnt(2)
	v_lshlrev_b32_e32 v184, 16, v186
	s_waitcnt lgkmcnt(1)
	v_lshlrev_b32_e32 v188, 16, v2
	v_and_b32_e32 v189, 0xffff0000, v2
	v_lshlrev_b32_e32 v190, 16, v3
	v_and_b32_e32 v191, 0xffff0000, v3
	ds_read2st64_b32 v[2:3], v238 offset0:112 offset1:116
	v_and_b32_e32 v185, 0xffff0000, v186
	v_lshlrev_b32_e32 v186, 16, v187
	v_and_b32_e32 v187, 0xffff0000, v187
	ds_read2st64_b32 v[202:203], v238 offset0:120 offset1:124
	s_waitcnt lgkmcnt(1)
	v_lshlrev_b32_e32 v196, 16, v2
	v_and_b32_e32 v197, 0xffff0000, v2
	v_lshlrev_b32_e32 v198, 16, v3
	v_and_b32_e32 v199, 0xffff0000, v3
	v_pk_fma_f32 v[2:3], v[122:123], v[204:205], v[128:129]
	v_lshlrev_b32_e32 v192, 16, v194
	v_pk_fma_f32 v[2:3], v[124:125], v[156:157], v[2:3]
	ds_read2st64_b32 v[208:209], v238 offset0:128 offset1:132
	ds_read2st64_b32 v[210:211], v238 offset0:136 offset1:140
	ds_read2st64_b32 v[204:205], v238 offset0:144 offset1:148
	v_pk_fma_f32 v[156:157], v[122:123], v[156:157], v[128:129]
	v_and_b32_e32 v193, 0xffff0000, v194
	v_pk_fma_f32 v[2:3], v[126:127], v[158:159], v[2:3]
	v_lshlrev_b32_e32 v194, 16, v195
	v_pk_fma_f32 v[2:3], v[120:121], v[164:165], v[2:3]
	v_and_b32_e32 v195, 0xffff0000, v195
	v_pk_fma_f32 v[2:3], v[80:81], v[148:149], v[2:3]
	s_waitcnt lgkmcnt(0)
	v_lshlrev_b32_e32 v200, 16, v202
	v_pk_fma_f32 v[2:3], v[82:83], v[150:151], v[2:3]
	v_and_b32_e32 v201, 0xffff0000, v202
	v_lshlrev_b32_e32 v202, 16, v203
	v_pk_fma_f32 v[156:157], v[124:125], v[158:159], v[156:157]
	v_pk_fma_f32 v[2:3], v[84:85], v[152:153], v[2:3]
	v_and_b32_e32 v203, 0xffff0000, v203
	v_pk_fma_f32 v[156:157], v[126:127], v[164:165], v[156:157]
	v_pk_fma_f32 v[2:3], v[86:87], v[4:5], v[2:3]
	v_pk_fma_f32 v[156:157], v[120:121], v[148:149], v[156:157]
	v_pk_fma_f32 v[2:3], v[88:89], v[6:7], v[2:3]
	v_pk_fma_f32 v[156:157], v[80:81], v[150:151], v[156:157]
	v_pk_fma_f32 v[2:3], v[90:91], v[8:9], v[2:3]
	v_pk_fma_f32 v[156:157], v[82:83], v[152:153], v[156:157]
	v_pk_fma_f32 v[2:3], v[92:93], v[154:155], v[2:3]
	v_pk_fma_f32 v[156:157], v[84:85], v[4:5], v[156:157]
	v_pk_fma_f32 v[2:3], v[94:95], v[160:161], v[2:3]
	v_pk_fma_f32 v[156:157], v[86:87], v[6:7], v[156:157]
	v_pk_fma_f32 v[2:3], v[96:97], v[162:163], v[2:3]
	v_pk_fma_f32 v[156:157], v[88:89], v[8:9], v[156:157]
	v_pk_fma_f32 v[2:3], v[98:99], v[166:167], v[2:3]
	v_pk_fma_f32 v[156:157], v[90:91], v[154:155], v[156:157]
	v_pk_fma_f32 v[2:3], v[100:101], v[168:169], v[2:3]
	v_pk_fma_f32 v[156:157], v[92:93], v[160:161], v[156:157]
	v_pk_fma_f32 v[2:3], v[102:103], v[170:171], v[2:3]
	v_pk_fma_f32 v[156:157], v[94:95], v[162:163], v[156:157]
	v_pk_fma_f32 v[2:3], v[104:105], v[172:173], v[2:3]
	v_pk_fma_f32 v[156:157], v[96:97], v[166:167], v[156:157]
	v_pk_fma_f32 v[2:3], v[106:107], v[174:175], v[2:3]
	v_pk_fma_f32 v[156:157], v[98:99], v[168:169], v[156:157]
	v_pk_fma_f32 v[2:3], v[108:109], v[176:177], v[2:3]
	v_pk_fma_f32 v[156:157], v[100:101], v[170:171], v[156:157]
	v_pk_fma_f32 v[2:3], v[110:111], v[178:179], v[2:3]
	v_pk_fma_f32 v[156:157], v[102:103], v[172:173], v[156:157]
	v_pk_fma_f32 v[2:3], v[112:113], v[180:181], v[2:3]
	v_pk_fma_f32 v[156:157], v[104:105], v[174:175], v[156:157]
; DI void conv_item(const Params& p, char* lds, int t0, int tid) {
;     ...
;     for (int i = 0; i < 8; ++i) {
;       float a = bias.x, b = bias.y;
; #pragma unroll
;       for (int j = 0; j < 31; ++j) { a += wa[j] * za[i + j]; b += wb[j] * zb[i + j]; }
;       ya[i] = a; yb[i] = b;
;     }
; #pragma unroll
;     for (int i = 0; i < 8; ++i) {
;       float s1 = wave_sum(ya[i] + yb[i]);
;       float s2 = wave_sum(ya[i] * ya[i] + yb[i] * yb[i]);
;       if (lane == 0) { red[(w * 8 + i) * 2] = s1; red[(w * 8 + i) * 2 + 1] = s2; }
;     }
	v_pk_fma_f32 v[2:3], v[114:115], v[182:183], v[2:3]
	v_pk_fma_f32 v[156:157], v[106:107], v[176:177], v[156:157]
	v_pk_fma_f32 v[2:3], v[116:117], v[184:185], v[2:3]
	v_pk_fma_f32 v[156:157], v[108:109], v[178:179], v[156:157]
	v_pk_fma_f32 v[2:3], v[118:119], v[186:187], v[2:3]
	v_pk_fma_f32 v[156:157], v[110:111], v[180:181], v[156:157]
	v_pk_fma_f32 v[2:3], v[130:131], v[188:189], v[2:3]
	v_pk_fma_f32 v[156:157], v[112:113], v[182:183], v[156:157]
	v_pk_fma_f32 v[2:3], v[132:133], v[190:191], v[2:3]
	v_pk_fma_f32 v[156:157], v[114:115], v[184:185], v[156:157]
	v_pk_fma_f32 v[2:3], v[134:135], v[192:193], v[2:3]
	v_pk_fma_f32 v[156:157], v[116:117], v[186:187], v[156:157]
	v_pk_fma_f32 v[2:3], v[136:137], v[194:195], v[2:3]
	v_pk_fma_f32 v[156:157], v[118:119], v[188:189], v[156:157]
	v_pk_fma_f32 v[2:3], v[138:139], v[196:197], v[2:3]
	v_pk_fma_f32 v[156:157], v[130:131], v[190:191], v[156:157]
	v_pk_fma_f32 v[2:3], v[140:141], v[198:199], v[2:3]
	v_pk_fma_f32 v[156:157], v[132:133], v[192:193], v[156:157]
	v_pk_fma_f32 v[2:3], v[142:143], v[200:201], v[2:3]
	v_pk_fma_f32 v[156:157], v[134:135], v[194:195], v[156:157]
	s_nop 0
	v_pk_fma_f32 v[156:157], v[136:137], v[196:197], v[156:157]
	s_nop 0
	v_pk_fma_f32 v[156:157], v[138:139], v[198:199], v[156:157]
	s_nop 0
	v_pk_fma_f32 v[156:157], v[140:141], v[200:201], v[156:157]
	s_nop 0
	v_pk_fma_f32 v[156:157], v[142:143], v[202:203], v[156:157]
	s_nop 0
	v_pk_mul_f32 v[250:251], v[2:3], v[2:3]
	v_pk_mul_f32 v[252:253], v[156:157], v[156:157]
	v_add_f32_e32 v240, v2, v3
	v_add_f32_e32 v244, v156, v157
	v_add_f32_e32 v241, v250, v251
	v_add_f32_e32 v245, v252, v253
	ds_bpermute_b32 v242, v222, v240
	ds_bpermute_b32 v243, v222, v241
	ds_bpermute_b32 v248, v222, v244
	ds_bpermute_b32 v249, v222, v245
	s_waitcnt lgkmcnt(2)
	v_pk_add_f32 v[240:241], v[240:241], v[242:243]
	s_waitcnt lgkmcnt(0)
	v_pk_add_f32 v[244:245], v[244:245], v[248:249]
	ds_bpermute_b32 v242, v223, v240
	ds_bpermute_b32 v243, v223, v241
	ds_bpermute_b32 v248, v223, v244
	ds_bpermute_b32 v249, v223, v245
	s_waitcnt lgkmcnt(2)
	v_pk_add_f32 v[240:241], v[240:241], v[242:243]
	s_waitcnt lgkmcnt(0)
	v_pk_add_f32 v[244:245], v[244:245], v[248:249]
	ds_bpermute_b32 v242, v224, v240
	ds_bpermute_b32 v243, v224, v241
	ds_bpermute_b32 v248, v224, v244
	ds_bpermute_b32 v249, v224, v245
	s_waitcnt lgkmcnt(2)
	v_pk_add_f32 v[240:241], v[240:241], v[242:243]
	s_waitcnt lgkmcnt(0)
	v_pk_add_f32 v[244:245], v[244:245], v[248:249]
	ds_bpermute_b32 v242, v225, v240
	ds_bpermute_b32 v243, v225, v241
	ds_bpermute_b32 v248, v225, v244
	ds_bpermute_b32 v249, v225, v245
	s_waitcnt lgkmcnt(2)
	v_pk_add_f32 v[240:241], v[240:241], v[242:243]
	s_waitcnt lgkmcnt(0)
	v_pk_add_f32 v[244:245], v[244:245], v[248:249]
	ds_bpermute_b32 v242, v226, v240
	ds_bpermute_b32 v243, v226, v241
	ds_bpermute_b32 v248, v226, v244
	ds_bpermute_b32 v249, v226, v245
	s_waitcnt lgkmcnt(2)
	v_pk_add_f32 v[240:241], v[240:241], v[242:243]
	s_waitcnt lgkmcnt(0)
	v_pk_add_f32 v[244:245], v[244:245], v[248:249]
	ds_bpermute_b32 v242, v227, v240
	ds_bpermute_b32 v243, v227, v241
	ds_bpermute_b32 v248, v227, v244
	ds_bpermute_b32 v249, v227, v245
	s_waitcnt lgkmcnt(2)
	v_pk_add_f32 v[240:241], v[240:241], v[242:243]
	s_waitcnt lgkmcnt(0)
	v_pk_add_f32 v[244:245], v[244:245], v[248:249]
	s_and_saveexec_b64 s[6:7], s[4:5]
	ds_write_b64 v228, v[240:241] offset:63488
	ds_write_b64 v228, v[244:245] offset:63496
	s_or_b64 exec, exec, s[6:7]
	v_pk_fma_f32 v[158:159], v[122:123], v[158:159], v[128:129]
	v_lshlrev_b32_e32 v206, 16, v208
	v_pk_fma_f32 v[158:159], v[124:125], v[164:165], v[158:159]
	v_pk_fma_f32 v[164:165], v[122:123], v[164:165], v[128:129]
	v_and_b32_e32 v207, 0xffff0000, v208
	v_pk_fma_f32 v[158:159], v[126:127], v[148:149], v[158:159]
	v_lshlrev_b32_e32 v208, 16, v209
	v_pk_fma_f32 v[164:165], v[124:125], v[148:149], v[164:165]
	v_pk_fma_f32 v[158:159], v[120:121], v[150:151], v[158:159]
	v_and_b32_e32 v209, 0xffff0000, v209
	v_pk_fma_f32 v[164:165], v[126:127], v[150:151], v[164:165]
	v_pk_fma_f32 v[158:159], v[80:81], v[152:153], v[158:159]
	v_pk_fma_f32 v[164:165], v[120:121], v[152:153], v[164:165]
	v_pk_fma_f32 v[158:159], v[82:83], v[4:5], v[158:159]
	v_pk_fma_f32 v[164:165], v[80:81], v[4:5], v[164:165]
	v_pk_fma_f32 v[158:159], v[84:85], v[6:7], v[158:159]
	v_pk_fma_f32 v[164:165], v[82:83], v[6:7], v[164:165]
	v_pk_fma_f32 v[158:159], v[86:87], v[8:9], v[158:159]
	v_pk_fma_f32 v[164:165], v[84:85], v[8:9], v[164:165]
	v_pk_fma_f32 v[158:159], v[88:89], v[154:155], v[158:159]
	v_pk_fma_f32 v[164:165], v[86:87], v[154:155], v[164:165]
	v_pk_fma_f32 v[158:159], v[90:91], v[160:161], v[158:159]
	v_pk_fma_f32 v[164:165], v[88:89], v[160:161], v[164:165]
	v_pk_fma_f32 v[158:159], v[92:93], v[162:163], v[158:159]
	v_pk_fma_f32 v[164:165], v[90:91], v[162:163], v[164:165]
	v_pk_fma_f32 v[158:159], v[94:95], v[166:167], v[158:159]
	v_pk_fma_f32 v[164:165], v[92:93], v[166:167], v[164:165]
	v_pk_fma_f32 v[158:159], v[96:97], v[168:169], v[158:159]
	v_pk_fma_f32 v[164:165], v[94:95], v[168:169], v[164:165]
	v_pk_fma_f32 v[158:159], v[98:99], v[170:171], v[158:159]
	v_pk_fma_f32 v[164:165], v[96:97], v[170:171], v[164:165]
	v_pk_fma_f32 v[158:159], v[100:101], v[172:173], v[158:159]
	v_pk_fma_f32 v[164:165], v[98:99], v[172:173], v[164:165]
	v_pk_fma_f32 v[158:159], v[102:103], v[174:175], v[158:159]
	v_pk_fma_f32 v[164:165], v[100:101], v[174:175], v[164:165]
	v_pk_fma_f32 v[158:159], v[104:105], v[176:177], v[158:159]
	v_pk_fma_f32 v[164:165], v[102:103], v[176:177], v[164:165]
	v_pk_fma_f32 v[158:159], v[106:107], v[178:179], v[158:159]
; DI void conv_item(const Params& p, char* lds, int t0, int tid) {
;     ...
;     for (int i = 0; i < 8; ++i) {
;       float a = bias.x, b = bias.y;
; #pragma unroll
;       for (int j = 0; j < 31; ++j) { a += wa[j] * za[i + j]; b += wb[j] * zb[i + j]; }
;       ya[i] = a; yb[i] = b;
;     }
; #pragma unroll
;     for (int i = 0; i < 8; ++i) {
;       float s1 = wave_sum(ya[i] + yb[i]);
;       float s2 = wave_sum(ya[i] * ya[i] + yb[i] * yb[i]);
;       if (lane == 0) { red[(w * 8 + i) * 2] = s1; red[(w * 8 + i) * 2 + 1] = s2; }
;     }
	v_pk_fma_f32 v[164:165], v[104:105], v[178:179], v[164:165]
	v_pk_fma_f32 v[158:159], v[108:109], v[180:181], v[158:159]
	v_pk_fma_f32 v[164:165], v[106:107], v[180:181], v[164:165]
	v_pk_fma_f32 v[158:159], v[110:111], v[182:183], v[158:159]
	v_pk_fma_f32 v[164:165], v[108:109], v[182:183], v[164:165]
	v_pk_fma_f32 v[158:159], v[112:113], v[184:185], v[158:159]
	v_pk_fma_f32 v[164:165], v[110:111], v[184:185], v[164:165]
	v_pk_fma_f32 v[158:159], v[114:115], v[186:187], v[158:159]
	v_pk_fma_f32 v[164:165], v[112:113], v[186:187], v[164:165]
	v_pk_fma_f32 v[158:159], v[116:117], v[188:189], v[158:159]
	v_pk_fma_f32 v[164:165], v[114:115], v[188:189], v[164:165]
	v_pk_fma_f32 v[158:159], v[118:119], v[190:191], v[158:159]
	v_pk_fma_f32 v[164:165], v[116:117], v[190:191], v[164:165]
	v_pk_fma_f32 v[158:159], v[130:131], v[192:193], v[158:159]
	v_pk_fma_f32 v[164:165], v[118:119], v[192:193], v[164:165]
	v_pk_fma_f32 v[158:159], v[132:133], v[194:195], v[158:159]
	v_pk_fma_f32 v[164:165], v[130:131], v[194:195], v[164:165]
	v_pk_fma_f32 v[158:159], v[134:135], v[196:197], v[158:159]
	v_pk_fma_f32 v[164:165], v[132:133], v[196:197], v[164:165]
	v_pk_fma_f32 v[158:159], v[136:137], v[198:199], v[158:159]
	v_pk_fma_f32 v[164:165], v[134:135], v[198:199], v[164:165]
	v_pk_fma_f32 v[158:159], v[138:139], v[200:201], v[158:159]
	v_pk_fma_f32 v[164:165], v[136:137], v[200:201], v[164:165]
	v_pk_fma_f32 v[158:159], v[140:141], v[202:203], v[158:159]
	v_pk_fma_f32 v[164:165], v[138:139], v[202:203], v[164:165]
	v_pk_fma_f32 v[158:159], v[142:143], v[206:207], v[158:159]
	v_pk_fma_f32 v[164:165], v[140:141], v[206:207], v[164:165]
	s_nop 0
	v_pk_fma_f32 v[164:165], v[142:143], v[208:209], v[164:165]
	s_nop 0
	v_pk_mul_f32 v[250:251], v[158:159], v[158:159]
	v_pk_mul_f32 v[252:253], v[164:165], v[164:165]
	v_add_f32_e32 v240, v158, v159
	v_add_f32_e32 v244, v164, v165
	v_add_f32_e32 v241, v250, v251
	v_add_f32_e32 v245, v252, v253
	ds_bpermute_b32 v242, v222, v240
	ds_bpermute_b32 v243, v222, v241
	ds_bpermute_b32 v248, v222, v244
	ds_bpermute_b32 v249, v222, v245
	s_waitcnt lgkmcnt(2)
	v_pk_add_f32 v[240:241], v[240:241], v[242:243]
	s_waitcnt lgkmcnt(0)
	v_pk_add_f32 v[244:245], v[244:245], v[248:249]
	ds_bpermute_b32 v242, v223, v240
	ds_bpermute_b32 v243, v223, v241
	ds_bpermute_b32 v248, v223, v244
	ds_bpermute_b32 v249, v223, v245
	s_waitcnt lgkmcnt(2)
	v_pk_add_f32 v[240:241], v[240:241], v[242:243]
	s_waitcnt lgkmcnt(0)
	v_pk_add_f32 v[244:245], v[244:245], v[248:249]
	ds_bpermute_b32 v242, v224, v240
	ds_bpermute_b32 v243, v224, v241
	ds_bpermute_b32 v248, v224, v244
	ds_bpermute_b32 v249, v224, v245
	s_waitcnt lgkmcnt(2)
	v_pk_add_f32 v[240:241], v[240:241], v[242:243]
	s_waitcnt lgkmcnt(0)
	v_pk_add_f32 v[244:245], v[244:245], v[248:249]
	ds_bpermute_b32 v242, v225, v240
	ds_bpermute_b32 v243, v225, v241
	ds_bpermute_b32 v248, v225, v244
	ds_bpermute_b32 v249, v225, v245
	s_waitcnt lgkmcnt(2)
	v_pk_add_f32 v[240:241], v[240:241], v[242:243]
	s_waitcnt lgkmcnt(0)
	v_pk_add_f32 v[244:245], v[244:245], v[248:249]
	ds_bpermute_b32 v242, v226, v240
	ds_bpermute_b32 v243, v226, v241
	ds_bpermute_b32 v248, v226, v244
	ds_bpermute_b32 v249, v226, v245
	s_waitcnt lgkmcnt(2)
	v_pk_add_f32 v[240:241], v[240:241], v[242:243]
	s_waitcnt lgkmcnt(0)
	v_pk_add_f32 v[244:245], v[244:245], v[248:249]
	ds_bpermute_b32 v242, v227, v240
	ds_bpermute_b32 v243, v227, v241
	ds_bpermute_b32 v248, v227, v244
	ds_bpermute_b32 v249, v227, v245
	s_waitcnt lgkmcnt(2)
	v_pk_add_f32 v[240:241], v[240:241], v[242:243]
	s_waitcnt lgkmcnt(0)
	v_pk_add_f32 v[244:245], v[244:245], v[248:249]
	s_and_saveexec_b64 s[6:7], s[4:5]
	ds_write_b64 v228, v[240:241] offset:63504
	ds_write_b64 v228, v[244:245] offset:63512
	s_or_b64 exec, exec, s[6:7]
	v_pk_fma_f32 v[148:149], v[122:123], v[148:149], v[128:129]
	v_lshlrev_b32_e32 v212, 16, v210
	v_pk_fma_f32 v[148:149], v[124:125], v[150:151], v[148:149]
	v_pk_fma_f32 v[150:151], v[122:123], v[150:151], v[128:129]
	v_and_b32_e32 v213, 0xffff0000, v210
	v_pk_fma_f32 v[148:149], v[126:127], v[152:153], v[148:149]
	v_lshlrev_b32_e32 v210, 16, v211
	v_pk_fma_f32 v[150:151], v[124:125], v[152:153], v[150:151]
	v_pk_fma_f32 v[148:149], v[120:121], v[4:5], v[148:149]
	v_and_b32_e32 v211, 0xffff0000, v211
	v_pk_fma_f32 v[150:151], v[126:127], v[4:5], v[150:151]
	v_pk_fma_f32 v[148:149], v[80:81], v[6:7], v[148:149]
	v_pk_fma_f32 v[150:151], v[120:121], v[6:7], v[150:151]
	v_pk_fma_f32 v[148:149], v[82:83], v[8:9], v[148:149]
	v_pk_fma_f32 v[150:151], v[80:81], v[8:9], v[150:151]
	v_pk_fma_f32 v[148:149], v[84:85], v[154:155], v[148:149]
	v_pk_fma_f32 v[150:151], v[82:83], v[154:155], v[150:151]
	v_pk_fma_f32 v[148:149], v[86:87], v[160:161], v[148:149]
	v_pk_fma_f32 v[150:151], v[84:85], v[160:161], v[150:151]
	v_pk_fma_f32 v[148:149], v[88:89], v[162:163], v[148:149]
	v_pk_fma_f32 v[150:151], v[86:87], v[162:163], v[150:151]
	v_pk_fma_f32 v[148:149], v[90:91], v[166:167], v[148:149]
	v_pk_fma_f32 v[150:151], v[88:89], v[166:167], v[150:151]
	v_pk_fma_f32 v[148:149], v[92:93], v[168:169], v[148:149]
	v_pk_fma_f32 v[150:151], v[90:91], v[168:169], v[150:151]
	v_pk_fma_f32 v[148:149], v[94:95], v[170:171], v[148:149]
	v_pk_fma_f32 v[150:151], v[92:93], v[170:171], v[150:151]
	v_pk_fma_f32 v[148:149], v[96:97], v[172:173], v[148:149]
	v_pk_fma_f32 v[150:151], v[94:95], v[172:173], v[150:151]
	v_pk_fma_f32 v[148:149], v[98:99], v[174:175], v[148:149]
	v_pk_fma_f32 v[150:151], v[96:97], v[174:175], v[150:151]
	v_pk_fma_f32 v[148:149], v[100:101], v[176:177], v[148:149]
	v_pk_fma_f32 v[150:151], v[98:99], v[176:177], v[150:151]
; DI void conv_item(const Params& p, char* lds, int t0, int tid) {
;     ...
;     for (int i = 0; i < 8; ++i) {
;       float a = bias.x, b = bias.y;
; #pragma unroll
;       for (int j = 0; j < 31; ++j) { a += wa[j] * za[i + j]; b += wb[j] * zb[i + j]; }
;       ya[i] = a; yb[i] = b;
;     }
; #pragma unroll
;     for (int i = 0; i < 8; ++i) {
;       float s1 = wave_sum(ya[i] + yb[i]);
;       float s2 = wave_sum(ya[i] * ya[i] + yb[i] * yb[i]);
;       if (lane == 0) { red[(w * 8 + i) * 2] = s1; red[(w * 8 + i) * 2 + 1] = s2; }
;     }
	v_pk_fma_f32 v[148:149], v[102:103], v[178:179], v[148:149]
	v_pk_fma_f32 v[150:151], v[100:101], v[178:179], v[150:151]
	v_pk_fma_f32 v[148:149], v[104:105], v[180:181], v[148:149]
	v_pk_fma_f32 v[150:151], v[102:103], v[180:181], v[150:151]
	v_pk_fma_f32 v[148:149], v[106:107], v[182:183], v[148:149]
	v_pk_fma_f32 v[150:151], v[104:105], v[182:183], v[150:151]
	v_pk_fma_f32 v[148:149], v[108:109], v[184:185], v[148:149]
	v_pk_fma_f32 v[150:151], v[106:107], v[184:185], v[150:151]
	v_pk_fma_f32 v[148:149], v[110:111], v[186:187], v[148:149]
	v_pk_fma_f32 v[150:151], v[108:109], v[186:187], v[150:151]
	v_pk_fma_f32 v[148:149], v[112:113], v[188:189], v[148:149]
	v_pk_fma_f32 v[150:151], v[110:111], v[188:189], v[150:151]
	v_pk_fma_f32 v[148:149], v[114:115], v[190:191], v[148:149]
	v_pk_fma_f32 v[150:151], v[112:113], v[190:191], v[150:151]
	v_pk_fma_f32 v[148:149], v[116:117], v[192:193], v[148:149]
	v_pk_fma_f32 v[150:151], v[114:115], v[192:193], v[150:151]
	v_pk_fma_f32 v[148:149], v[118:119], v[194:195], v[148:149]
	v_pk_fma_f32 v[150:151], v[116:117], v[194:195], v[150:151]
	v_pk_fma_f32 v[148:149], v[130:131], v[196:197], v[148:149]
	v_pk_fma_f32 v[150:151], v[118:119], v[196:197], v[150:151]
	v_pk_fma_f32 v[148:149], v[132:133], v[198:199], v[148:149]
	v_pk_fma_f32 v[150:151], v[130:131], v[198:199], v[150:151]
	v_pk_fma_f32 v[148:149], v[134:135], v[200:201], v[148:149]
	v_pk_fma_f32 v[150:151], v[132:133], v[200:201], v[150:151]
	v_pk_fma_f32 v[148:149], v[136:137], v[202:203], v[148:149]
	v_pk_fma_f32 v[150:151], v[134:135], v[202:203], v[150:151]
	v_pk_fma_f32 v[148:149], v[138:139], v[206:207], v[148:149]
	v_pk_fma_f32 v[150:151], v[136:137], v[206:207], v[150:151]
	v_pk_fma_f32 v[148:149], v[140:141], v[208:209], v[148:149]
	v_pk_fma_f32 v[150:151], v[138:139], v[208:209], v[150:151]
	v_pk_fma_f32 v[148:149], v[142:143], v[212:213], v[148:149]
	v_pk_fma_f32 v[150:151], v[140:141], v[212:213], v[150:151]
	s_nop 0
	v_pk_fma_f32 v[150:151], v[142:143], v[210:211], v[150:151]
	s_nop 0
	v_pk_mul_f32 v[250:251], v[148:149], v[148:149]
	v_pk_mul_f32 v[252:253], v[150:151], v[150:151]
	v_add_f32_e32 v240, v148, v149
	v_add_f32_e32 v244, v150, v151
	v_add_f32_e32 v241, v250, v251
	v_add_f32_e32 v245, v252, v253
	ds_bpermute_b32 v242, v222, v240
	ds_bpermute_b32 v243, v222, v241
	ds_bpermute_b32 v248, v222, v244
	ds_bpermute_b32 v249, v222, v245
	s_waitcnt lgkmcnt(2)
	v_pk_add_f32 v[240:241], v[240:241], v[242:243]
	s_waitcnt lgkmcnt(0)
	v_pk_add_f32 v[244:245], v[244:245], v[248:249]
	ds_bpermute_b32 v242, v223, v240
	ds_bpermute_b32 v243, v223, v241
	ds_bpermute_b32 v248, v223, v244
	ds_bpermute_b32 v249, v223, v245
	s_waitcnt lgkmcnt(2)
	v_pk_add_f32 v[240:241], v[240:241], v[242:243]
	s_waitcnt lgkmcnt(0)
	v_pk_add_f32 v[244:245], v[244:245], v[248:249]
	ds_bpermute_b32 v242, v224, v240
	ds_bpermute_b32 v243, v224, v241
	ds_bpermute_b32 v248, v224, v244
	ds_bpermute_b32 v249, v224, v245
	s_waitcnt lgkmcnt(2)
	v_pk_add_f32 v[240:241], v[240:241], v[242:243]
	s_waitcnt lgkmcnt(0)
	v_pk_add_f32 v[244:245], v[244:245], v[248:249]
	ds_bpermute_b32 v242, v225, v240
	ds_bpermute_b32 v243, v225, v241
	ds_bpermute_b32 v248, v225, v244
	ds_bpermute_b32 v249, v225, v245
	s_waitcnt lgkmcnt(2)
	v_pk_add_f32 v[240:241], v[240:241], v[242:243]
	s_waitcnt lgkmcnt(0)
	v_pk_add_f32 v[244:245], v[244:245], v[248:249]
	ds_bpermute_b32 v242, v226, v240
	ds_bpermute_b32 v243, v226, v241
	ds_bpermute_b32 v248, v226, v244
	ds_bpermute_b32 v249, v226, v245
	s_waitcnt lgkmcnt(2)
	v_pk_add_f32 v[240:241], v[240:241], v[242:243]
	s_waitcnt lgkmcnt(0)
	v_pk_add_f32 v[244:245], v[244:245], v[248:249]
	ds_bpermute_b32 v242, v227, v240
	ds_bpermute_b32 v243, v227, v241
	ds_bpermute_b32 v248, v227, v244
	ds_bpermute_b32 v249, v227, v245
	s_waitcnt lgkmcnt(2)
	v_pk_add_f32 v[240:241], v[240:241], v[242:243]
	s_waitcnt lgkmcnt(0)
; DI void conv_item(const Params& p, char* lds, int t0, int tid) {
;     ...
;     for (int i = 0; i < 8; ++i) {
;       float a = bias.x, b = bias.y;
; #pragma unroll
;       for (int j = 0; j < 31; ++j) { a += wa[j] * za[i + j]; b += wb[j] * zb[i + j]; }
;       ya[i] = a; yb[i] = b;
;     }
; #pragma unroll
;     for (int i = 0; i < 8; ++i) {
;       float s1 = wave_sum(ya[i] + yb[i]);
;       float s2 = wave_sum(ya[i] * ya[i] + yb[i] * yb[i]);
;       if (lane == 0) { red[(w * 8 + i) * 2] = s1; red[(w * 8 + i) * 2 + 1] = s2; }
;     }
	v_pk_add_f32 v[244:245], v[244:245], v[248:249]
	s_and_saveexec_b64 s[6:7], s[4:5]
	ds_write_b64 v228, v[240:241] offset:63520
	ds_write_b64 v228, v[244:245] offset:63528
	s_or_b64 exec, exec, s[6:7]
	v_pk_fma_f32 v[152:153], v[122:123], v[152:153], v[128:129]
	v_lshlrev_b32_e32 v214, 16, v204
	v_pk_fma_f32 v[152:153], v[124:125], v[4:5], v[152:153]
	v_pk_fma_f32 v[4:5], v[122:123], v[4:5], v[128:129]
	v_and_b32_e32 v215, 0xffff0000, v204
	v_pk_fma_f32 v[152:153], v[126:127], v[6:7], v[152:153]
	v_lshlrev_b32_e32 v204, 16, v205
	v_pk_fma_f32 v[4:5], v[124:125], v[6:7], v[4:5]
	v_pk_fma_f32 v[152:153], v[120:121], v[8:9], v[152:153]
	v_and_b32_e32 v205, 0xffff0000, v205
	v_pk_fma_f32 v[4:5], v[126:127], v[8:9], v[4:5]
	v_pk_fma_f32 v[152:153], v[80:81], v[154:155], v[152:153]
	v_pk_fma_f32 v[4:5], v[120:121], v[154:155], v[4:5]
	v_pk_fma_f32 v[152:153], v[82:83], v[160:161], v[152:153]
	v_pk_fma_f32 v[4:5], v[80:81], v[160:161], v[4:5]
	v_pk_fma_f32 v[152:153], v[84:85], v[162:163], v[152:153]
	v_pk_fma_f32 v[4:5], v[82:83], v[162:163], v[4:5]
	v_pk_fma_f32 v[152:153], v[86:87], v[166:167], v[152:153]
	v_pk_fma_f32 v[4:5], v[84:85], v[166:167], v[4:5]
	v_pk_fma_f32 v[152:153], v[88:89], v[168:169], v[152:153]
	v_pk_fma_f32 v[4:5], v[86:87], v[168:169], v[4:5]
	v_pk_fma_f32 v[152:153], v[90:91], v[170:171], v[152:153]
	v_pk_fma_f32 v[4:5], v[88:89], v[170:171], v[4:5]
	v_pk_fma_f32 v[152:153], v[92:93], v[172:173], v[152:153]
	v_pk_fma_f32 v[4:5], v[90:91], v[172:173], v[4:5]
	v_pk_fma_f32 v[152:153], v[94:95], v[174:175], v[152:153]
	v_pk_fma_f32 v[4:5], v[92:93], v[174:175], v[4:5]
	v_pk_fma_f32 v[152:153], v[96:97], v[176:177], v[152:153]
	v_pk_fma_f32 v[4:5], v[94:95], v[176:177], v[4:5]
	v_pk_fma_f32 v[152:153], v[98:99], v[178:179], v[152:153]
	v_pk_fma_f32 v[4:5], v[96:97], v[178:179], v[4:5]
	v_pk_fma_f32 v[152:153], v[100:101], v[180:181], v[152:153]
	v_pk_fma_f32 v[4:5], v[98:99], v[180:181], v[4:5]
	v_pk_fma_f32 v[152:153], v[102:103], v[182:183], v[152:153]
	v_pk_fma_f32 v[4:5], v[100:101], v[182:183], v[4:5]
	v_pk_fma_f32 v[152:153], v[104:105], v[184:185], v[152:153]
	v_pk_fma_f32 v[4:5], v[102:103], v[184:185], v[4:5]
	v_pk_fma_f32 v[152:153], v[106:107], v[186:187], v[152:153]
	v_pk_fma_f32 v[4:5], v[104:105], v[186:187], v[4:5]
	v_pk_fma_f32 v[152:153], v[108:109], v[188:189], v[152:153]
	v_pk_fma_f32 v[4:5], v[106:107], v[188:189], v[4:5]
	v_pk_fma_f32 v[152:153], v[110:111], v[190:191], v[152:153]
	v_pk_fma_f32 v[4:5], v[108:109], v[190:191], v[4:5]
	v_pk_fma_f32 v[152:153], v[112:113], v[192:193], v[152:153]
	v_pk_fma_f32 v[4:5], v[110:111], v[192:193], v[4:5]
	v_pk_fma_f32 v[152:153], v[114:115], v[194:195], v[152:153]
	v_pk_fma_f32 v[4:5], v[112:113], v[194:195], v[4:5]
	v_pk_fma_f32 v[152:153], v[116:117], v[196:197], v[152:153]
	v_pk_fma_f32 v[4:5], v[114:115], v[196:197], v[4:5]
	v_pk_fma_f32 v[152:153], v[118:119], v[198:199], v[152:153]
	v_pk_fma_f32 v[4:5], v[116:117], v[198:199], v[4:5]
	v_pk_fma_f32 v[152:153], v[130:131], v[200:201], v[152:153]
	v_pk_fma_f32 v[4:5], v[118:119], v[200:201], v[4:5]
	v_pk_fma_f32 v[152:153], v[132:133], v[202:203], v[152:153]
	v_pk_fma_f32 v[4:5], v[130:131], v[202:203], v[4:5]
	v_pk_fma_f32 v[152:153], v[134:135], v[206:207], v[152:153]
	v_pk_fma_f32 v[4:5], v[132:133], v[206:207], v[4:5]
	v_pk_fma_f32 v[152:153], v[136:137], v[208:209], v[152:153]
	v_pk_fma_f32 v[4:5], v[134:135], v[208:209], v[4:5]
	v_pk_fma_f32 v[152:153], v[138:139], v[212:213], v[152:153]
	v_pk_fma_f32 v[4:5], v[136:137], v[212:213], v[4:5]
	v_pk_fma_f32 v[152:153], v[140:141], v[210:211], v[152:153]
	v_pk_fma_f32 v[4:5], v[138:139], v[210:211], v[4:5]
	v_pk_fma_f32 v[152:153], v[142:143], v[214:215], v[152:153]
	v_pk_fma_f32 v[4:5], v[140:141], v[214:215], v[4:5]
	s_nop 0
	v_pk_fma_f32 v[154:155], v[142:143], v[204:205], v[4:5]
	s_nop 0
	v_pk_mul_f32 v[250:251], v[152:153], v[152:153]
	v_pk_mul_f32 v[252:253], v[154:155], v[154:155]
	v_add_f32_e32 v240, v152, v153
	v_add_f32_e32 v244, v154, v155
	v_add_f32_e32 v241, v250, v251
	v_add_f32_e32 v245, v252, v253
	ds_bpermute_b32 v242, v222, v240
	ds_bpermute_b32 v243, v222, v241
	ds_bpermute_b32 v248, v222, v244
	ds_bpermute_b32 v249, v222, v245
	s_waitcnt lgkmcnt(2)
	v_pk_add_f32 v[240:241], v[240:241], v[242:243]
	s_waitcnt lgkmcnt(0)
	v_pk_add_f32 v[244:245], v[244:245], v[248:249]
	ds_bpermute_b32 v242, v223, v240
	ds_bpermute_b32 v243, v223, v241
	ds_bpermute_b32 v248, v223, v244
	ds_bpermute_b32 v249, v223, v245
	s_waitcnt lgkmcnt(2)
	v_pk_add_f32 v[240:241], v[240:241], v[242:243]
	s_waitcnt lgkmcnt(0)
	v_pk_add_f32 v[244:245], v[244:245], v[248:249]
	ds_bpermute_b32 v242, v224, v240
	ds_bpermute_b32 v243, v224, v241
	ds_bpermute_b32 v248, v224, v244
	ds_bpermute_b32 v249, v224, v245
	s_waitcnt lgkmcnt(2)
	v_pk_add_f32 v[240:241], v[240:241], v[242:243]
	s_waitcnt lgkmcnt(0)
	v_pk_add_f32 v[244:245], v[244:245], v[248:249]
	ds_bpermute_b32 v242, v225, v240
	ds_bpermute_b32 v243, v225, v241
	ds_bpermute_b32 v248, v225, v244
	ds_bpermute_b32 v249, v225, v245
	s_waitcnt lgkmcnt(2)
	v_pk_add_f32 v[240:241], v[240:241], v[242:243]
	s_waitcnt lgkmcnt(0)
	v_pk_add_f32 v[244:245], v[244:245], v[248:249]
	ds_bpermute_b32 v242, v226, v240
	ds_bpermute_b32 v243, v226, v241
	ds_bpermute_b32 v248, v226, v244
	ds_bpermute_b32 v249, v226, v245
	s_waitcnt lgkmcnt(2)
	v_pk_add_f32 v[240:241], v[240:241], v[242:243]
	s_waitcnt lgkmcnt(0)
	v_pk_add_f32 v[244:245], v[244:245], v[248:249]
	ds_bpermute_b32 v242, v227, v240
	ds_bpermute_b32 v243, v227, v241
	ds_bpermute_b32 v248, v227, v244
	ds_bpermute_b32 v249, v227, v245
	s_waitcnt lgkmcnt(2)
	v_pk_add_f32 v[240:241], v[240:241], v[242:243]
	s_waitcnt lgkmcnt(0)
	v_pk_add_f32 v[244:245], v[244:245], v[248:249]
	s_and_saveexec_b64 s[6:7], s[4:5]
	ds_write_b64 v228, v[240:241] offset:63536
	ds_write_b64 v228, v[244:245] offset:63544
	s_branch .LBB0_195
